# v25 + store-completion waits removed in rw_pre loop + fast iteration added to ca_q and ca_o GEMM loops
# baseline (speedup 1.0000x reference)
; DEV float bf2f(bf16_t b) { return __uint_as_float(((unsigned)b) << 16); }
; DEV void phase_rw_pre(const Params& p) {
;     ...
;       const int hc = h * 64 + lane;
;       float x = bf2f(raw[h][0]);
;       const float r = x + p.in[14][hc] * ((hp ? bf2f(raw[h][1]) : 0.f) - x) + p.in[15][hc] * ((hn ? bf2f(raw[h][2]) : 0.f) - x);
;       x = bf2f(raw[h][3]);
;       const float kr = x + p.in[14][512 + hc] * ((hp ? bf2f(raw[h][4]) : 0.f) - x) + p.in[15][512 + hc] * ((hn ? bf2f(raw[h][5]) : 0.f) - x);
;       const float a = bf2f(raw[h][6]);
;       const float kkr = kr * p.in[23][hc];
;       const float inv = rsqrtf(fmaxf(wave_sum_dpp(kkr * kkr), 1e-24f));
;       const float kk = kkr * inv;
;       const float k2 = kr * (1.f + (a - 1.f) * p.in[24][hc]);
;       const float kar = wave_sum_dpp(kk * a * r);
;       const float bo = wave_sum_dpp(r * k2 * p.in[25][hc]);
.LBB0_1847:
	s_and_saveexec_b64 s[78:79], s[6:7]
	s_cbranch_execz .LBB0_1866
	global_load_dword v110, v[6:7], off
	global_load_dword v111, v[8:9], off
	global_load_dword v112, v[6:7], off offset:2048
	global_load_dword v113, v[8:9], off offset:2048
	global_load_dword v114, v[12:13], off
	global_load_dword v115, v[10:11], off
	global_load_dword v116, v[14:15], off
	global_load_dword v117, v[6:7], off offset:256
	global_load_dword v118, v[8:9], off offset:256
	global_load_dword v119, v[12:13], off offset:256
	global_load_dword v120, v[6:7], off offset:2304
	global_load_dword v121, v[8:9], off offset:2304
	global_load_dword v122, v[10:11], off offset:256
	global_load_dword v123, v[14:15], off offset:256
	global_load_dword v124, v[6:7], off offset:512
	global_load_dword v125, v[8:9], off offset:512
	global_load_dword v126, v[12:13], off offset:512
	global_load_dword v127, v[6:7], off offset:2560
	global_load_dword v128, v[8:9], off offset:2560
	global_load_dword v129, v[10:11], off offset:512
	global_load_dword v130, v[14:15], off offset:512
	global_load_dword v131, v[6:7], off offset:768
	global_load_dword v132, v[8:9], off offset:768
	global_load_dword v133, v[12:13], off offset:768
	global_load_dword v134, v[6:7], off offset:2816
	global_load_dword v136, v[8:9], off offset:2816
	global_load_dword v137, v[10:11], off offset:768
	global_load_dword v138, v[14:15], off offset:768
	global_load_dword v139, v[6:7], off offset:1024
	global_load_dword v142, v[8:9], off offset:1024
	global_load_dword v143, v[12:13], off offset:1024
	global_load_dword v144, v[6:7], off offset:3072
	global_load_dword v145, v[8:9], off offset:3072
	global_load_dword v146, v[10:11], off offset:1024
	global_load_dword v147, v[14:15], off offset:1024
	global_load_dword v148, v[6:7], off offset:1280
	global_load_dword v149, v[8:9], off offset:1280
	global_load_dword v150, v[12:13], off offset:1280
	global_load_dword v151, v[6:7], off offset:3328
	global_load_dword v152, v[8:9], off offset:3328
	global_load_dword v153, v[10:11], off offset:1280
	global_load_dword v154, v[14:15], off offset:1280
	global_load_dword v155, v[6:7], off offset:1536
	global_load_dword v156, v[8:9], off offset:1536
	global_load_dword v157, v[12:13], off offset:1536
	global_load_dword v158, v[6:7], off offset:3584
	global_load_dword v159, v[8:9], off offset:3584
	global_load_dword v160, v[10:11], off offset:1536
	global_load_dword v161, v[14:15], off offset:1536
	global_load_dword v162, v[6:7], off offset:1792
	global_load_dword v163, v[8:9], off offset:1792
	global_load_dword v164, v[12:13], off offset:1792
	global_load_dword v165, v[10:11], off offset:1792
	global_load_dword v166, v[14:15], off offset:1792
	global_load_dword v169, v[16:17], off
	global_load_dword v170, v[18:19], off
	s_waitcnt vmcnt(0)
	s_mov_b64 s[84:85], 0
	v_mov_b64_e32 v[26:27], v[20:21]
	v_mov_b64_e32 v[28:29], v[24:25]
	v_mov_b64_e32 v[30:31], v[22:23]
	v_mov_b32_e32 v49, v4
	s_branch .LBB0_1850

; DEV float bf2f(bf16_t b) { return __uint_as_float(((unsigned)b) << 16); }
; DEV void phase_rw_pre(const Params& p) {
;     ...
;     for (int h = 0; h < 8; ++h) {
;       const int hc = h * 64 + lane;
;       float x = bf2f(raw[h][0]);
;       const float r = x + p.in[14][hc] * ((hp ? bf2f(raw[h][1]) : 0.f) - x) + p.in[15][hc] * ((hn ? bf2f(raw[h][2]) : 0.f) - x);
;       x = bf2f(raw[h][3]);
;       const float kr = x + p.in[14][512 + hc] * ((hp ? bf2f(raw[h][4]) : 0.f) - x) + p.in[15][512 + hc] * ((hn ? bf2f(raw[h][5]) : 0.f) - x);
;       const float a = bf2f(raw[h][6]);
;       const float kkr = kr * p.in[23][hc];
;       const float inv = rsqrtf(fmaxf(wave_sum_dpp(kkr * kkr), 1e-24f));
;       const float kk = kkr * inv;
;       const float k2 = kr * (1.f + (a - 1.f) * p.in[24][hc]);
;       const float kar = wave_sum_dpp(kk * a * r);
;       const float bo = wave_sum_dpp(r * k2 * p.in[25][hc]);
;       if (lane == 0) *(float4*)(scal + ((size_t)t * 8 + h) * 4) = make_float4(inv, kar, bo, 0.f);
.LBB0_1852:
	s_or_b64 exec, exec, s[90:91]
	s_nop 0
	v_mov_b32_e32 v0, v117
	v_lshlrev_b32_e32 v2, 16, v97
	v_mov_b32_e32 v34, v118
	v_lshlrev_b32_e32 v1, 16, v95
	v_cndmask_b32_e64 v2, 0, v2, s[12:13]
	v_lshlrev_b32_e32 v35, 16, v98
	v_sub_f32_e32 v2, v2, v1
	v_cndmask_b32_e64 v35, 0, v35, s[14:15]
	v_sub_f32_e32 v35, v35, v1
	v_lshlrev_b32_e32 v36, 16, v93
	v_cndmask_b32_e64 v36, 0, v36, s[14:15]
	v_mov_b32_e32 v37, v119
	v_fmac_f32_e32 v1, v2, v0
	v_mov_b32_e32 v0, v120
	v_fmac_f32_e32 v1, v35, v34
	v_lshlrev_b32_e32 v34, 16, v94
	v_lshlrev_b32_e32 v2, 16, v96
	v_cndmask_b32_e64 v34, 0, v34, s[12:13]
	v_sub_f32_e32 v34, v34, v2
	v_mov_b32_e32 v35, v121
	v_sub_f32_e32 v36, v36, v2
	v_fmac_f32_e32 v2, v34, v0
	v_mov_b32_e32 v0, v122
	v_lshlrev_b32_e32 v34, 16, v92
	v_fmac_f32_e32 v2, v36, v35
	v_mul_f32_e32 v35, v0, v2
	v_mul_f32_e32 v0, v35, v35
	s_nop 1
	v_mov_b32_dpp v0, v0 row_ror:8 row_mask:0xf bank_mask:0xf bound_ctrl:1
	v_fmac_f32_e32 v0, v35, v35
	s_nop 1
	v_add_f32_dpp v0, v0, v0 row_ror:4 row_mask:0xf bank_mask:0xf bound_ctrl:1
	s_nop 1
	v_add_f32_dpp v0, v0, v0 row_ror:2 row_mask:0xf bank_mask:0xf bound_ctrl:1
	s_nop 1
	v_add_f32_dpp v0, v0, v0 row_ror:1 row_mask:0xf bank_mask:0xf bound_ctrl:1
	s_nop 0
	v_readlane_b32 s72, v0, 16
	v_readlane_b32 s87, v0, 48
	v_readlane_b32 s1, v0, 0
	v_readlane_b32 s86, v0, 32
	v_mov_b32_e32 v0, s72
	v_mov_b32_e32 v36, s87
	v_add_f32_e32 v0, s1, v0
	v_add_f32_e32 v36, s86, v36
	v_add_f32_e32 v0, v0, v36
	v_max_f32_e32 v0, 0x179abe15, v0
	v_rsq_f32_e32 v0, v0
	v_add_f32_e32 v36, -1.0, v34
	v_fma_f32 v36, v36, v37, 1.0
	v_mul_f32_e32 v2, v2, v36
	v_mul_f32_e32 v35, v35, v0
	v_mul_f32_e32 v34, v35, v34
	v_mul_f32_e32 v35, v1, v34
	s_nop 1
	v_mov_b32_dpp v35, v35 row_ror:8 row_mask:0xf bank_mask:0xf bound_ctrl:1
	v_fmac_f32_e32 v35, v1, v34
	v_mul_f32_e32 v1, v1, v2
	v_mov_b32_e32 v2, v123
	v_add_f32_dpp v34, v35, v35 row_ror:4 row_mask:0xf bank_mask:0xf bound_ctrl:1
	s_nop 1
	v_add_f32_dpp v34, v34, v34 row_ror:2 row_mask:0xf bank_mask:0xf bound_ctrl:1
	s_nop 1
	v_add_f32_dpp v34, v34, v34 row_ror:1 row_mask:0xf bank_mask:0xf bound_ctrl:1
	s_nop 0
	v_readlane_b32 s86, v34, 0
	v_readlane_b32 s72, v34, 16
	v_readlane_b32 s88, v34, 32
	v_readlane_b32 s1, v34, 48
	v_mul_f32_e32 v34, v1, v2
	s_nop 1
	v_mov_b32_dpp v34, v34 row_ror:8 row_mask:0xf bank_mask:0xf bound_ctrl:1
	v_fmac_f32_e32 v34, v1, v2
	s_nop 1
	v_add_f32_dpp v1, v34, v34 row_ror:4 row_mask:0xf bank_mask:0xf bound_ctrl:1
	s_nop 1
	v_add_f32_dpp v1, v1, v1 row_ror:2 row_mask:0xf bank_mask:0xf bound_ctrl:1
	s_nop 1
	v_add_f32_dpp v1, v1, v1 row_ror:1 row_mask:0xf bank_mask:0xf bound_ctrl:1
	s_nop 0
	v_readlane_b32 s87, v1, 0
	v_readlane_b32 s92, v1, 16
	v_readlane_b32 s89, v1, 32
	v_readlane_b32 s93, v1, 48
	s_and_saveexec_b64 s[90:91], s[8:9]
	s_cbranch_execz .LBB0_1854
	v_mov_b32_e32 v34, s72
	v_mov_b32_e32 v35, s92
	v_mov_b32_e32 v36, s1
	v_mov_b32_e32 v37, s93
	v_pk_add_f32 v[34:35], s[86:87], v[34:35]
	v_pk_add_f32 v[36:37], s[88:89], v[36:37]
	s_nop 0
	v_pk_add_f32 v[34:35], v[34:35], v[36:37]
	s_nop 0
	v_mov_b32_e32 v1, v34
	v_add_co_u32_e32 v34, vcc, 0x1c500000, v32
	v_mov_b32_e32 v2, v35
	s_nop 0
	v_addc_co_u32_e32 v35, vcc, 0, v33, vcc
	global_store_dwordx4 v[34:35], v[0:3], off offset:16
.LBB0_1854:
	s_or_b64 exec, exec, s[90:91]
	s_nop 0
	v_mov_b32_e32 v0, v124
	v_lshlrev_b32_e32 v2, 16, v90
	v_mov_b32_e32 v34, v125
	v_lshlrev_b32_e32 v1, 16, v91
	v_cndmask_b32_e64 v2, 0, v2, s[12:13]
	v_lshlrev_b32_e32 v35, 16, v89
	v_sub_f32_e32 v2, v2, v1
	v_cndmask_b32_e64 v35, 0, v35, s[14:15]
	v_sub_f32_e32 v35, v35, v1
	v_lshlrev_b32_e32 v36, 16, v86
	v_cndmask_b32_e64 v36, 0, v36, s[14:15]
	v_mov_b32_e32 v37, v126
	v_fmac_f32_e32 v1, v2, v0
	v_mov_b32_e32 v0, v127
	v_fmac_f32_e32 v1, v35, v34
	v_lshlrev_b32_e32 v34, 16, v87
	v_lshlrev_b32_e32 v2, 16, v88
	v_cndmask_b32_e64 v34, 0, v34, s[12:13]
	v_sub_f32_e32 v34, v34, v2
	v_mov_b32_e32 v35, v128
	v_sub_f32_e32 v36, v36, v2
	v_fmac_f32_e32 v2, v34, v0
	v_mov_b32_e32 v0, v129
	v_lshlrev_b32_e32 v34, 16, v85
	v_fmac_f32_e32 v2, v36, v35
	v_mul_f32_e32 v35, v0, v2
	v_mul_f32_e32 v0, v35, v35
	s_nop 1
	v_mov_b32_dpp v0, v0 row_ror:8 row_mask:0xf bank_mask:0xf bound_ctrl:1
	v_fmac_f32_e32 v0, v35, v35
	s_nop 1
	v_add_f32_dpp v0, v0, v0 row_ror:4 row_mask:0xf bank_mask:0xf bound_ctrl:1
	s_nop 1
	v_add_f32_dpp v0, v0, v0 row_ror:2 row_mask:0xf bank_mask:0xf bound_ctrl:1
	s_nop 1
	v_add_f32_dpp v0, v0, v0 row_ror:1 row_mask:0xf bank_mask:0xf bound_ctrl:1
	s_nop 0
	v_readlane_b32 s72, v0, 16
	v_readlane_b32 s87, v0, 48
	v_readlane_b32 s1, v0, 0
	v_readlane_b32 s86, v0, 32
	v_mov_b32_e32 v0, s72
	v_mov_b32_e32 v36, s87
	v_add_f32_e32 v0, s1, v0
	v_add_f32_e32 v36, s86, v36
	v_add_f32_e32 v0, v0, v36
	v_max_f32_e32 v0, 0x179abe15, v0
	v_rsq_f32_e32 v0, v0
	v_add_f32_e32 v36, -1.0, v34
	v_fma_f32 v36, v36, v37, 1.0
	v_mul_f32_e32 v2, v2, v36
	v_mul_f32_e32 v35, v35, v0
	v_mul_f32_e32 v34, v35, v34
	v_mul_f32_e32 v35, v1, v34
	s_nop 1
	v_mov_b32_dpp v35, v35 row_ror:8 row_mask:0xf bank_mask:0xf bound_ctrl:1
	v_fmac_f32_e32 v35, v1, v34
	v_mul_f32_e32 v1, v1, v2
	v_mov_b32_e32 v2, v130
	v_add_f32_dpp v34, v35, v35 row_ror:4 row_mask:0xf bank_mask:0xf bound_ctrl:1
	s_nop 1
	v_add_f32_dpp v34, v34, v34 row_ror:2 row_mask:0xf bank_mask:0xf bound_ctrl:1
	s_nop 1
	v_add_f32_dpp v34, v34, v34 row_ror:1 row_mask:0xf bank_mask:0xf bound_ctrl:1
	s_nop 0
	v_readlane_b32 s86, v34, 0
	v_readlane_b32 s72, v34, 16
	v_readlane_b32 s88, v34, 32
	v_readlane_b32 s1, v34, 48
	v_mul_f32_e32 v34, v1, v2
	s_nop 1
	v_mov_b32_dpp v34, v34 row_ror:8 row_mask:0xf bank_mask:0xf bound_ctrl:1
	v_fmac_f32_e32 v34, v1, v2
	s_nop 1
	v_add_f32_dpp v1, v34, v34 row_ror:4 row_mask:0xf bank_mask:0xf bound_ctrl:1
	s_nop 1
	v_add_f32_dpp v1, v1, v1 row_ror:2 row_mask:0xf bank_mask:0xf bound_ctrl:1
	s_nop 1
	v_add_f32_dpp v1, v1, v1 row_ror:1 row_mask:0xf bank_mask:0xf bound_ctrl:1
	s_nop 0
	v_readlane_b32 s87, v1, 0
	v_readlane_b32 s92, v1, 16
	v_readlane_b32 s89, v1, 32
	v_readlane_b32 s93, v1, 48
	s_and_saveexec_b64 s[90:91], s[8:9]
	s_cbranch_execz .LBB0_1856
	v_mov_b32_e32 v34, s72
	v_mov_b32_e32 v35, s92
	v_mov_b32_e32 v36, s1
	v_mov_b32_e32 v37, s93
	v_pk_add_f32 v[34:35], s[86:87], v[34:35]
	v_pk_add_f32 v[36:37], s[88:89], v[36:37]
	s_nop 0
	v_pk_add_f32 v[34:35], v[34:35], v[36:37]
	s_nop 0
	v_mov_b32_e32 v1, v34
	v_add_co_u32_e32 v34, vcc, 0x1c500000, v32
	v_mov_b32_e32 v2, v35
	s_nop 0
	v_addc_co_u32_e32 v35, vcc, 0, v33, vcc
	global_store_dwordx4 v[34:35], v[0:3], off offset:32
; DEV float bf2f(bf16_t b) { return __uint_as_float(((unsigned)b) << 16); }
; DEV void phase_rw_pre(const Params& p) {
;     ...
;     for (int h = 0; h < 8; ++h) {
;       const int hc = h * 64 + lane;
;       float x = bf2f(raw[h][0]);
;       const float r = x + p.in[14][hc] * ((hp ? bf2f(raw[h][1]) : 0.f) - x) + p.in[15][hc] * ((hn ? bf2f(raw[h][2]) : 0.f) - x);
;       x = bf2f(raw[h][3]);
;       const float kr = x + p.in[14][512 + hc] * ((hp ? bf2f(raw[h][4]) : 0.f) - x) + p.in[15][512 + hc] * ((hn ? bf2f(raw[h][5]) : 0.f) - x);
;       const float a = bf2f(raw[h][6]);
;       const float kkr = kr * p.in[23][hc];
;       const float inv = rsqrtf(fmaxf(wave_sum_dpp(kkr * kkr), 1e-24f));
;       const float kk = kkr * inv;
;       const float k2 = kr * (1.f + (a - 1.f) * p.in[24][hc]);
;       const float kar = wave_sum_dpp(kk * a * r);
;       const float bo = wave_sum_dpp(r * k2 * p.in[25][hc]);
;       if (lane == 0) *(float4*)(scal + ((size_t)t * 8 + h) * 4) = make_float4(inv, kar, bo, 0.f);
.LBB0_1856:
	s_or_b64 exec, exec, s[90:91]
	s_nop 0
	v_mov_b32_e32 v0, v131
	v_lshlrev_b32_e32 v2, 16, v83
	v_mov_b32_e32 v34, v132
	v_lshlrev_b32_e32 v1, 16, v84
	v_cndmask_b32_e64 v2, 0, v2, s[12:13]
	v_lshlrev_b32_e32 v35, 16, v82
	v_sub_f32_e32 v2, v2, v1
	v_cndmask_b32_e64 v35, 0, v35, s[14:15]
	v_sub_f32_e32 v35, v35, v1
	v_lshlrev_b32_e32 v36, 16, v79
	v_cndmask_b32_e64 v36, 0, v36, s[14:15]
	v_mov_b32_e32 v37, v133
	v_fmac_f32_e32 v1, v2, v0
	v_mov_b32_e32 v0, v134
	v_fmac_f32_e32 v1, v35, v34
	v_lshlrev_b32_e32 v34, 16, v80
	v_lshlrev_b32_e32 v2, 16, v81
	v_cndmask_b32_e64 v34, 0, v34, s[12:13]
	v_sub_f32_e32 v34, v34, v2
	v_mov_b32_e32 v35, v136
	v_sub_f32_e32 v36, v36, v2
	v_fmac_f32_e32 v2, v34, v0
	v_mov_b32_e32 v0, v137
	v_lshlrev_b32_e32 v34, 16, v78
	v_fmac_f32_e32 v2, v36, v35
	v_mul_f32_e32 v35, v0, v2
	v_mul_f32_e32 v0, v35, v35
	s_nop 1
	v_mov_b32_dpp v0, v0 row_ror:8 row_mask:0xf bank_mask:0xf bound_ctrl:1
	v_fmac_f32_e32 v0, v35, v35
	s_nop 1
	v_add_f32_dpp v0, v0, v0 row_ror:4 row_mask:0xf bank_mask:0xf bound_ctrl:1
	s_nop 1
	v_add_f32_dpp v0, v0, v0 row_ror:2 row_mask:0xf bank_mask:0xf bound_ctrl:1
	s_nop 1
	v_add_f32_dpp v0, v0, v0 row_ror:1 row_mask:0xf bank_mask:0xf bound_ctrl:1
	s_nop 0
	v_readlane_b32 s72, v0, 16
	v_readlane_b32 s87, v0, 48
	v_readlane_b32 s1, v0, 0
	v_readlane_b32 s86, v0, 32
	v_mov_b32_e32 v0, s72
	v_mov_b32_e32 v36, s87
	v_add_f32_e32 v0, s1, v0
	v_add_f32_e32 v36, s86, v36
	v_add_f32_e32 v0, v0, v36
	v_max_f32_e32 v0, 0x179abe15, v0
	v_rsq_f32_e32 v0, v0
	v_add_f32_e32 v36, -1.0, v34
	v_fma_f32 v36, v36, v37, 1.0
	v_mul_f32_e32 v2, v2, v36
	v_mul_f32_e32 v35, v35, v0
	v_mul_f32_e32 v34, v35, v34
	v_mul_f32_e32 v35, v1, v34
	s_nop 1
	v_mov_b32_dpp v35, v35 row_ror:8 row_mask:0xf bank_mask:0xf bound_ctrl:1
	v_fmac_f32_e32 v35, v1, v34
	v_mul_f32_e32 v1, v1, v2
	v_mov_b32_e32 v2, v138
	v_add_f32_dpp v34, v35, v35 row_ror:4 row_mask:0xf bank_mask:0xf bound_ctrl:1
	s_nop 1
	v_add_f32_dpp v34, v34, v34 row_ror:2 row_mask:0xf bank_mask:0xf bound_ctrl:1
	s_nop 1
	v_add_f32_dpp v34, v34, v34 row_ror:1 row_mask:0xf bank_mask:0xf bound_ctrl:1
	s_nop 0
	v_readlane_b32 s86, v34, 0
	v_readlane_b32 s72, v34, 16
	v_readlane_b32 s88, v34, 32
	v_readlane_b32 s1, v34, 48
	v_mul_f32_e32 v34, v1, v2
	s_nop 1
	v_mov_b32_dpp v34, v34 row_ror:8 row_mask:0xf bank_mask:0xf bound_ctrl:1
	v_fmac_f32_e32 v34, v1, v2
	s_nop 1
	v_add_f32_dpp v1, v34, v34 row_ror:4 row_mask:0xf bank_mask:0xf bound_ctrl:1
	s_nop 1
	v_add_f32_dpp v1, v1, v1 row_ror:2 row_mask:0xf bank_mask:0xf bound_ctrl:1
	s_nop 1
	v_add_f32_dpp v1, v1, v1 row_ror:1 row_mask:0xf bank_mask:0xf bound_ctrl:1
	s_nop 0
	v_readlane_b32 s87, v1, 0
	v_readlane_b32 s92, v1, 16
	v_readlane_b32 s89, v1, 32
	v_readlane_b32 s93, v1, 48
	s_and_saveexec_b64 s[90:91], s[8:9]
	s_cbranch_execz .LBB0_1858
	v_mov_b32_e32 v34, s72
	v_mov_b32_e32 v35, s92
	v_mov_b32_e32 v36, s1
	v_mov_b32_e32 v37, s93
	v_pk_add_f32 v[34:35], s[86:87], v[34:35]
	v_pk_add_f32 v[36:37], s[88:89], v[36:37]
	s_nop 0
	v_pk_add_f32 v[34:35], v[34:35], v[36:37]
	s_nop 0
	v_mov_b32_e32 v1, v34
	v_add_co_u32_e32 v34, vcc, 0x1c500000, v32
	v_mov_b32_e32 v2, v35
	s_nop 0
	v_addc_co_u32_e32 v35, vcc, 0, v33, vcc
	global_store_dwordx4 v[34:35], v[0:3], off offset:48
.LBB0_1858:
	s_or_b64 exec, exec, s[90:91]
	s_nop 0
	v_mov_b32_e32 v0, v139
	v_lshlrev_b32_e32 v2, 16, v76
	v_mov_b32_e32 v34, v142
	v_lshlrev_b32_e32 v1, 16, v77
	v_cndmask_b32_e64 v2, 0, v2, s[12:13]
	v_lshlrev_b32_e32 v35, 16, v75
	v_sub_f32_e32 v2, v2, v1
	v_cndmask_b32_e64 v35, 0, v35, s[14:15]
	v_sub_f32_e32 v35, v35, v1
	v_lshlrev_b32_e32 v36, 16, v72
	v_cndmask_b32_e64 v36, 0, v36, s[14:15]
	v_mov_b32_e32 v37, v143
	v_fmac_f32_e32 v1, v2, v0
	v_mov_b32_e32 v0, v144
	v_fmac_f32_e32 v1, v35, v34
	v_lshlrev_b32_e32 v34, 16, v73
	v_lshlrev_b32_e32 v2, 16, v74
	v_cndmask_b32_e64 v34, 0, v34, s[12:13]
	v_sub_f32_e32 v34, v34, v2
	v_mov_b32_e32 v35, v145
	v_sub_f32_e32 v36, v36, v2
	v_fmac_f32_e32 v2, v34, v0
	v_mov_b32_e32 v0, v146
	v_lshlrev_b32_e32 v34, 16, v71
	v_fmac_f32_e32 v2, v36, v35
	v_mul_f32_e32 v35, v0, v2
	v_mul_f32_e32 v0, v35, v35
	s_nop 1
	v_mov_b32_dpp v0, v0 row_ror:8 row_mask:0xf bank_mask:0xf bound_ctrl:1
	v_fmac_f32_e32 v0, v35, v35
	s_nop 1
	v_add_f32_dpp v0, v0, v0 row_ror:4 row_mask:0xf bank_mask:0xf bound_ctrl:1
	s_nop 1
	v_add_f32_dpp v0, v0, v0 row_ror:2 row_mask:0xf bank_mask:0xf bound_ctrl:1
	s_nop 1
	v_add_f32_dpp v0, v0, v0 row_ror:1 row_mask:0xf bank_mask:0xf bound_ctrl:1
	s_nop 0
	v_readlane_b32 s72, v0, 16
	v_readlane_b32 s87, v0, 48
	v_readlane_b32 s1, v0, 0
	v_readlane_b32 s86, v0, 32
	v_mov_b32_e32 v0, s72
	v_mov_b32_e32 v36, s87
	v_add_f32_e32 v0, s1, v0
	v_add_f32_e32 v36, s86, v36
	v_add_f32_e32 v0, v0, v36
	v_max_f32_e32 v0, 0x179abe15, v0
	v_rsq_f32_e32 v0, v0
	v_add_f32_e32 v36, -1.0, v34
	v_fma_f32 v36, v36, v37, 1.0
	v_mul_f32_e32 v2, v2, v36
	v_mul_f32_e32 v35, v35, v0
	v_mul_f32_e32 v34, v35, v34
	v_mul_f32_e32 v35, v1, v34
	s_nop 1
	v_mov_b32_dpp v35, v35 row_ror:8 row_mask:0xf bank_mask:0xf bound_ctrl:1
	v_fmac_f32_e32 v35, v1, v34
	v_mul_f32_e32 v1, v1, v2
	v_mov_b32_e32 v2, v147
	v_add_f32_dpp v34, v35, v35 row_ror:4 row_mask:0xf bank_mask:0xf bound_ctrl:1
	s_nop 1
	v_add_f32_dpp v34, v34, v34 row_ror:2 row_mask:0xf bank_mask:0xf bound_ctrl:1
	s_nop 1
	v_add_f32_dpp v34, v34, v34 row_ror:1 row_mask:0xf bank_mask:0xf bound_ctrl:1
	s_nop 0
	v_readlane_b32 s86, v34, 0
	v_readlane_b32 s72, v34, 16
	v_readlane_b32 s88, v34, 32
	v_readlane_b32 s1, v34, 48
	v_mul_f32_e32 v34, v1, v2
	s_nop 1
	v_mov_b32_dpp v34, v34 row_ror:8 row_mask:0xf bank_mask:0xf bound_ctrl:1
	v_fmac_f32_e32 v34, v1, v2
	s_nop 1
	v_add_f32_dpp v1, v34, v34 row_ror:4 row_mask:0xf bank_mask:0xf bound_ctrl:1
	s_nop 1
	v_add_f32_dpp v1, v1, v1 row_ror:2 row_mask:0xf bank_mask:0xf bound_ctrl:1
	s_nop 1
	v_add_f32_dpp v1, v1, v1 row_ror:1 row_mask:0xf bank_mask:0xf bound_ctrl:1
	s_nop 0
	v_readlane_b32 s87, v1, 0
	v_readlane_b32 s92, v1, 16
	v_readlane_b32 s89, v1, 32
	v_readlane_b32 s93, v1, 48
	s_and_saveexec_b64 s[90:91], s[8:9]
	s_cbranch_execz .LBB0_1860
	v_mov_b32_e32 v34, s72
	v_mov_b32_e32 v35, s92
	v_mov_b32_e32 v36, s1
	v_mov_b32_e32 v37, s93
	v_pk_add_f32 v[34:35], s[86:87], v[34:35]
	v_pk_add_f32 v[36:37], s[88:89], v[36:37]
	s_nop 0
	v_pk_add_f32 v[34:35], v[34:35], v[36:37]
	s_nop 0
	v_mov_b32_e32 v1, v34
	v_add_co_u32_e32 v34, vcc, 0x1c500000, v32
	v_mov_b32_e32 v2, v35
	s_nop 0
	v_addc_co_u32_e32 v35, vcc, 0, v33, vcc
	global_store_dwordx4 v[34:35], v[0:3], off offset:64
; DEV float bf2f(bf16_t b) { return __uint_as_float(((unsigned)b) << 16); }
; DEV void phase_rw_pre(const Params& p) {
;     ...
;     for (int h = 0; h < 8; ++h) {
;       const int hc = h * 64 + lane;
;       float x = bf2f(raw[h][0]);
;       const float r = x + p.in[14][hc] * ((hp ? bf2f(raw[h][1]) : 0.f) - x) + p.in[15][hc] * ((hn ? bf2f(raw[h][2]) : 0.f) - x);
;       x = bf2f(raw[h][3]);
;       const float kr = x + p.in[14][512 + hc] * ((hp ? bf2f(raw[h][4]) : 0.f) - x) + p.in[15][512 + hc] * ((hn ? bf2f(raw[h][5]) : 0.f) - x);
;       const float a = bf2f(raw[h][6]);
;       const float kkr = kr * p.in[23][hc];
;       const float inv = rsqrtf(fmaxf(wave_sum_dpp(kkr * kkr), 1e-24f));
;       const float kk = kkr * inv;
;       const float k2 = kr * (1.f + (a - 1.f) * p.in[24][hc]);
;       const float kar = wave_sum_dpp(kk * a * r);
;       const float bo = wave_sum_dpp(r * k2 * p.in[25][hc]);
;       if (lane == 0) *(float4*)(scal + ((size_t)t * 8 + h) * 4) = make_float4(inv, kar, bo, 0.f);
.LBB0_1860:
	s_or_b64 exec, exec, s[90:91]
	s_nop 0
	v_mov_b32_e32 v0, v148
	v_lshlrev_b32_e32 v2, 16, v69
	v_mov_b32_e32 v34, v149
	v_lshlrev_b32_e32 v1, 16, v70
	v_cndmask_b32_e64 v2, 0, v2, s[12:13]
	v_lshlrev_b32_e32 v35, 16, v68
	v_sub_f32_e32 v2, v2, v1
	v_cndmask_b32_e64 v35, 0, v35, s[14:15]
	v_sub_f32_e32 v35, v35, v1
	v_lshlrev_b32_e32 v36, 16, v65
	v_cndmask_b32_e64 v36, 0, v36, s[14:15]
	v_mov_b32_e32 v37, v150
	v_fmac_f32_e32 v1, v2, v0
	v_mov_b32_e32 v0, v151
	v_fmac_f32_e32 v1, v35, v34
	v_lshlrev_b32_e32 v34, 16, v66
	v_lshlrev_b32_e32 v2, 16, v67
	v_cndmask_b32_e64 v34, 0, v34, s[12:13]
	v_sub_f32_e32 v34, v34, v2
	v_mov_b32_e32 v35, v152
	v_sub_f32_e32 v36, v36, v2
	v_fmac_f32_e32 v2, v34, v0
	v_mov_b32_e32 v0, v153
	v_lshlrev_b32_e32 v34, 16, v64
	v_fmac_f32_e32 v2, v36, v35
	v_mul_f32_e32 v35, v0, v2
	v_mul_f32_e32 v0, v35, v35
	s_nop 1
	v_mov_b32_dpp v0, v0 row_ror:8 row_mask:0xf bank_mask:0xf bound_ctrl:1
	v_fmac_f32_e32 v0, v35, v35
	s_nop 1
	v_add_f32_dpp v0, v0, v0 row_ror:4 row_mask:0xf bank_mask:0xf bound_ctrl:1
	s_nop 1
	v_add_f32_dpp v0, v0, v0 row_ror:2 row_mask:0xf bank_mask:0xf bound_ctrl:1
	s_nop 1
	v_add_f32_dpp v0, v0, v0 row_ror:1 row_mask:0xf bank_mask:0xf bound_ctrl:1
	s_nop 0
	v_readlane_b32 s72, v0, 16
	v_readlane_b32 s87, v0, 48
	v_readlane_b32 s1, v0, 0
	v_readlane_b32 s86, v0, 32
	v_mov_b32_e32 v0, s72
	v_mov_b32_e32 v36, s87
	v_add_f32_e32 v0, s1, v0
	v_add_f32_e32 v36, s86, v36
	v_add_f32_e32 v0, v0, v36
	v_max_f32_e32 v0, 0x179abe15, v0
	v_rsq_f32_e32 v0, v0
	v_add_f32_e32 v36, -1.0, v34
	v_fma_f32 v36, v36, v37, 1.0
	v_mul_f32_e32 v2, v2, v36
	v_mul_f32_e32 v35, v35, v0
	v_mul_f32_e32 v34, v35, v34
	v_mul_f32_e32 v35, v1, v34
	s_nop 1
	v_mov_b32_dpp v35, v35 row_ror:8 row_mask:0xf bank_mask:0xf bound_ctrl:1
	v_fmac_f32_e32 v35, v1, v34
	v_mul_f32_e32 v1, v1, v2
	v_mov_b32_e32 v2, v154
	v_add_f32_dpp v34, v35, v35 row_ror:4 row_mask:0xf bank_mask:0xf bound_ctrl:1
	s_nop 1
	v_add_f32_dpp v34, v34, v34 row_ror:2 row_mask:0xf bank_mask:0xf bound_ctrl:1
	s_nop 1
	v_add_f32_dpp v34, v34, v34 row_ror:1 row_mask:0xf bank_mask:0xf bound_ctrl:1
	s_nop 0
	v_readlane_b32 s86, v34, 0
	v_readlane_b32 s72, v34, 16
	v_readlane_b32 s88, v34, 32
	v_readlane_b32 s1, v34, 48
	v_mul_f32_e32 v34, v1, v2
	s_nop 1
	v_mov_b32_dpp v34, v34 row_ror:8 row_mask:0xf bank_mask:0xf bound_ctrl:1
	v_fmac_f32_e32 v34, v1, v2
	s_nop 1
	v_add_f32_dpp v1, v34, v34 row_ror:4 row_mask:0xf bank_mask:0xf bound_ctrl:1
	s_nop 1
	v_add_f32_dpp v1, v1, v1 row_ror:2 row_mask:0xf bank_mask:0xf bound_ctrl:1
	s_nop 1
	v_add_f32_dpp v1, v1, v1 row_ror:1 row_mask:0xf bank_mask:0xf bound_ctrl:1
	s_nop 0
	v_readlane_b32 s87, v1, 0
	v_readlane_b32 s92, v1, 16
	v_readlane_b32 s89, v1, 32
	v_readlane_b32 s93, v1, 48
	s_and_saveexec_b64 s[90:91], s[8:9]
	s_cbranch_execz .LBB0_1862
	v_mov_b32_e32 v34, s72
	v_mov_b32_e32 v35, s92
	v_mov_b32_e32 v36, s1
	v_mov_b32_e32 v37, s93
	v_pk_add_f32 v[34:35], s[86:87], v[34:35]
	v_pk_add_f32 v[36:37], s[88:89], v[36:37]
	s_nop 0
	v_pk_add_f32 v[34:35], v[34:35], v[36:37]
	s_nop 0
	v_mov_b32_e32 v1, v34
	v_add_co_u32_e32 v34, vcc, 0x1c500000, v32
	v_mov_b32_e32 v2, v35
	s_nop 0
	v_addc_co_u32_e32 v35, vcc, 0, v33, vcc
	global_store_dwordx4 v[34:35], v[0:3], off offset:80
.LBB0_1862:
	s_or_b64 exec, exec, s[90:91]
	s_nop 0
	v_mov_b32_e32 v0, v155
	v_lshlrev_b32_e32 v2, 16, v62
	v_mov_b32_e32 v34, v156
	v_lshlrev_b32_e32 v1, 16, v63
	v_cndmask_b32_e64 v2, 0, v2, s[12:13]
	v_lshlrev_b32_e32 v35, 16, v61
	v_sub_f32_e32 v2, v2, v1
	v_cndmask_b32_e64 v35, 0, v35, s[14:15]
	v_sub_f32_e32 v35, v35, v1
	v_lshlrev_b32_e32 v36, 16, v58
	v_cndmask_b32_e64 v36, 0, v36, s[14:15]
	v_mov_b32_e32 v37, v157
	v_fmac_f32_e32 v1, v2, v0
	v_mov_b32_e32 v0, v158
	v_fmac_f32_e32 v1, v35, v34
	v_lshlrev_b32_e32 v34, 16, v59
	v_lshlrev_b32_e32 v2, 16, v60
	v_cndmask_b32_e64 v34, 0, v34, s[12:13]
	v_sub_f32_e32 v34, v34, v2
	v_mov_b32_e32 v35, v159
	v_sub_f32_e32 v36, v36, v2
	v_fmac_f32_e32 v2, v34, v0
	v_mov_b32_e32 v0, v160
	v_lshlrev_b32_e32 v34, 16, v57
	v_fmac_f32_e32 v2, v36, v35
	v_mul_f32_e32 v35, v0, v2
	v_mul_f32_e32 v0, v35, v35
	s_nop 1
	v_mov_b32_dpp v0, v0 row_ror:8 row_mask:0xf bank_mask:0xf bound_ctrl:1
	v_fmac_f32_e32 v0, v35, v35
	s_nop 1
	v_add_f32_dpp v0, v0, v0 row_ror:4 row_mask:0xf bank_mask:0xf bound_ctrl:1
	s_nop 1
	v_add_f32_dpp v0, v0, v0 row_ror:2 row_mask:0xf bank_mask:0xf bound_ctrl:1
	s_nop 1
	v_add_f32_dpp v0, v0, v0 row_ror:1 row_mask:0xf bank_mask:0xf bound_ctrl:1
	s_nop 0
	v_readlane_b32 s72, v0, 16
	v_readlane_b32 s87, v0, 48
	v_readlane_b32 s1, v0, 0
	v_readlane_b32 s86, v0, 32
	v_mov_b32_e32 v0, s72
	v_mov_b32_e32 v36, s87
	v_add_f32_e32 v0, s1, v0
	v_add_f32_e32 v36, s86, v36
	v_add_f32_e32 v0, v0, v36
	v_max_f32_e32 v0, 0x179abe15, v0
	v_rsq_f32_e32 v0, v0
	v_add_f32_e32 v36, -1.0, v34
	v_fma_f32 v36, v36, v37, 1.0
	v_mul_f32_e32 v2, v2, v36
	v_mul_f32_e32 v35, v35, v0
	v_mul_f32_e32 v34, v35, v34
	v_mul_f32_e32 v35, v1, v34
	s_nop 1
	v_mov_b32_dpp v35, v35 row_ror:8 row_mask:0xf bank_mask:0xf bound_ctrl:1
	v_fmac_f32_e32 v35, v1, v34
	v_mul_f32_e32 v1, v1, v2
	v_mov_b32_e32 v2, v161
	v_add_f32_dpp v34, v35, v35 row_ror:4 row_mask:0xf bank_mask:0xf bound_ctrl:1
	s_nop 1
	v_add_f32_dpp v34, v34, v34 row_ror:2 row_mask:0xf bank_mask:0xf bound_ctrl:1
	s_nop 1
	v_add_f32_dpp v34, v34, v34 row_ror:1 row_mask:0xf bank_mask:0xf bound_ctrl:1
	s_nop 0
	v_readlane_b32 s86, v34, 0
	v_readlane_b32 s72, v34, 16
	v_readlane_b32 s88, v34, 32
	v_readlane_b32 s1, v34, 48
	v_mul_f32_e32 v34, v1, v2
	s_nop 1
	v_mov_b32_dpp v34, v34 row_ror:8 row_mask:0xf bank_mask:0xf bound_ctrl:1
	v_fmac_f32_e32 v34, v1, v2
	s_nop 1
	v_add_f32_dpp v1, v34, v34 row_ror:4 row_mask:0xf bank_mask:0xf bound_ctrl:1
	s_nop 1
	v_add_f32_dpp v1, v1, v1 row_ror:2 row_mask:0xf bank_mask:0xf bound_ctrl:1
	s_nop 1
	v_add_f32_dpp v1, v1, v1 row_ror:1 row_mask:0xf bank_mask:0xf bound_ctrl:1
	s_nop 0
	v_readlane_b32 s87, v1, 0
	v_readlane_b32 s92, v1, 16
	v_readlane_b32 s89, v1, 32
	v_readlane_b32 s93, v1, 48
	s_and_saveexec_b64 s[90:91], s[8:9]
	s_cbranch_execz .LBB0_1864
	v_mov_b32_e32 v34, s72
	v_mov_b32_e32 v35, s92
	v_mov_b32_e32 v36, s1
	v_mov_b32_e32 v37, s93
	v_pk_add_f32 v[34:35], s[86:87], v[34:35]
	v_pk_add_f32 v[36:37], s[88:89], v[36:37]
	s_nop 0
	v_pk_add_f32 v[34:35], v[34:35], v[36:37]
	s_nop 0
	v_mov_b32_e32 v1, v34
	v_add_co_u32_e32 v34, vcc, 0x1c500000, v32
	v_mov_b32_e32 v2, v35
	s_nop 0
	v_addc_co_u32_e32 v35, vcc, 0, v33, vcc
	global_store_dwordx4 v[34:35], v[0:3], off offset:96
; DEV float bf2f(bf16_t b) { return __uint_as_float(((unsigned)b) << 16); }
; DEV void phase_rw_pre(const Params& p) {
;     ...
;     for (int h = 0; h < 8; ++h) {
;       const int hc = h * 64 + lane;
;       float x = bf2f(raw[h][0]);
;       const float r = x + p.in[14][hc] * ((hp ? bf2f(raw[h][1]) : 0.f) - x) + p.in[15][hc] * ((hn ? bf2f(raw[h][2]) : 0.f) - x);
;       x = bf2f(raw[h][3]);
;       const float kr = x + p.in[14][512 + hc] * ((hp ? bf2f(raw[h][4]) : 0.f) - x) + p.in[15][512 + hc] * ((hn ? bf2f(raw[h][5]) : 0.f) - x);
;       const float a = bf2f(raw[h][6]);
;       const float kkr = kr * p.in[23][hc];
;       const float inv = rsqrtf(fmaxf(wave_sum_dpp(kkr * kkr), 1e-24f));
;       const float kk = kkr * inv;
;       const float k2 = kr * (1.f + (a - 1.f) * p.in[24][hc]);
;       const float kar = wave_sum_dpp(kk * a * r);
;       const float bo = wave_sum_dpp(r * k2 * p.in[25][hc]);
;       if (lane == 0) *(float4*)(scal + ((size_t)t * 8 + h) * 4) = make_float4(inv, kar, bo, 0.f);
.LBB0_1864:
	s_or_b64 exec, exec, s[90:91]
	s_nop 0
	v_mov_b32_e32 v0, v162
	v_lshlrev_b32_e32 v2, 16, v55
	v_mov_b32_e32 v34, v163
	v_lshlrev_b32_e32 v1, 16, v56
	v_cndmask_b32_e64 v2, 0, v2, s[12:13]
	v_lshlrev_b32_e32 v35, 16, v54
	v_sub_f32_e32 v2, v2, v1
	v_cndmask_b32_e64 v35, 0, v35, s[14:15]
	v_sub_f32_e32 v35, v35, v1
	v_lshlrev_b32_e32 v36, 16, v51
	v_cndmask_b32_e64 v36, 0, v36, s[14:15]
	v_mov_b32_e32 v37, v164
	v_fmac_f32_e32 v1, v2, v0
	v_mov_b32_e32 v0, v169
	v_fmac_f32_e32 v1, v35, v34
	v_lshlrev_b32_e32 v34, 16, v52
	v_lshlrev_b32_e32 v2, 16, v53
	v_cndmask_b32_e64 v34, 0, v34, s[12:13]
	v_sub_f32_e32 v34, v34, v2
	v_mov_b32_e32 v35, v170
	v_sub_f32_e32 v36, v36, v2
	v_fmac_f32_e32 v2, v34, v0
	v_mov_b32_e32 v0, v165
	v_lshlrev_b32_e32 v34, 16, v50
	v_fmac_f32_e32 v2, v36, v35
	v_mul_f32_e32 v35, v0, v2
	v_mul_f32_e32 v0, v35, v35
	s_nop 1
	v_mov_b32_dpp v0, v0 row_ror:8 row_mask:0xf bank_mask:0xf bound_ctrl:1
	v_fmac_f32_e32 v0, v35, v35
	s_nop 1
	v_add_f32_dpp v0, v0, v0 row_ror:4 row_mask:0xf bank_mask:0xf bound_ctrl:1
	s_nop 1
	v_add_f32_dpp v0, v0, v0 row_ror:2 row_mask:0xf bank_mask:0xf bound_ctrl:1
	s_nop 1
	v_add_f32_dpp v0, v0, v0 row_ror:1 row_mask:0xf bank_mask:0xf bound_ctrl:1
	s_nop 0
	v_readlane_b32 s12, v0, 16
	v_readlane_b32 s14, v0, 48
	v_readlane_b32 s1, v0, 0
	v_readlane_b32 s13, v0, 32
	v_mov_b32_e32 v0, s12
	v_mov_b32_e32 v36, s14
	v_add_f32_e32 v0, s1, v0
	v_add_f32_e32 v36, s13, v36
	v_add_f32_e32 v0, v0, v36
	v_max_f32_e32 v0, 0x179abe15, v0
	v_rsq_f32_e32 v0, v0
	v_add_f32_e32 v36, -1.0, v34
	v_fma_f32 v36, v36, v37, 1.0
	v_mul_f32_e32 v2, v2, v36
	v_mul_f32_e32 v35, v35, v0
	v_mul_f32_e32 v34, v35, v34
	v_mul_f32_e32 v35, v1, v34
	s_nop 1
	v_mov_b32_dpp v35, v35 row_ror:8 row_mask:0xf bank_mask:0xf bound_ctrl:1
	v_fmac_f32_e32 v35, v1, v34
	v_mul_f32_e32 v1, v1, v2
	v_mov_b32_e32 v2, v166
	v_add_f32_dpp v34, v35, v35 row_ror:4 row_mask:0xf bank_mask:0xf bound_ctrl:1
	s_nop 1
	v_add_f32_dpp v34, v34, v34 row_ror:2 row_mask:0xf bank_mask:0xf bound_ctrl:1
	s_nop 1
	v_add_f32_dpp v34, v34, v34 row_ror:1 row_mask:0xf bank_mask:0xf bound_ctrl:1
	s_nop 0
	v_readlane_b32 s12, v34, 0
	v_readlane_b32 s72, v34, 16
	v_readlane_b32 s14, v34, 32
	v_readlane_b32 s1, v34, 48
	v_mul_f32_e32 v34, v1, v2
	s_nop 1
	v_mov_b32_dpp v34, v34 row_ror:8 row_mask:0xf bank_mask:0xf bound_ctrl:1
	v_fmac_f32_e32 v34, v1, v2
	s_nop 1
	v_add_f32_dpp v1, v34, v34 row_ror:4 row_mask:0xf bank_mask:0xf bound_ctrl:1
	s_nop 1
	v_add_f32_dpp v1, v1, v1 row_ror:2 row_mask:0xf bank_mask:0xf bound_ctrl:1
	s_nop 1
	v_add_f32_dpp v1, v1, v1 row_ror:1 row_mask:0xf bank_mask:0xf bound_ctrl:1
	s_nop 0
	v_readlane_b32 s13, v1, 0
	v_readlane_b32 s88, v1, 16
	v_readlane_b32 s15, v1, 32
	v_readlane_b32 s89, v1, 48
	s_and_saveexec_b64 s[86:87], s[8:9]
	s_cbranch_execz .LBB0_1849
	v_mov_b32_e32 v34, s72
	v_mov_b32_e32 v35, s88
	v_mov_b32_e32 v36, s1
	v_mov_b32_e32 v37, s89
	v_pk_add_f32 v[34:35], s[12:13], v[34:35]
	v_pk_add_f32 v[36:37], s[14:15], v[36:37]
	v_add_co_u32_e32 v32, vcc, 0x1c500000, v32
	v_pk_add_f32 v[34:35], v[34:35], v[36:37]
	s_nop 0
	v_addc_co_u32_e32 v33, vcc, 0, v33, vcc
	v_mov_b32_e32 v1, v34
	v_mov_b32_e32 v2, v35
	global_store_dwordx4 v[32:33], v[0:3], off offset:112
	s_branch .LBB0_1849

; template <bool RES, class Epi>
; DEV void gemm_tile_x(const bf16_t* A0, int lda0, const bf16_t* A1, int lda1, int ksplit,
;                      const bf16_t* Bt, int ldb, int K, char* smem, const float* resb, Epi epi) {
;     ...
;   for (int kt = 0; kt < nk; kt += 2) {
;     GEMM_COMPUTE(sbase);
;     if (kt + 1 < nk) gemm_lds_write(g1, sbase + GST + woff, sbase + GST + GSA + woff);
;     if (kt + 3 < nk) gemm_gload(g1, A0, lda0, A1, lda1, ksplit, Bt, ldb, (kt + 3) * 32, tid);
;     __syncthreads();
;     if (kt + 1 < nk) {
;       GEMM_COMPUTE(sbase + GST);
;       if (kt + 2 < nk) gemm_lds_write(g, sbase + woff, sbase + GSA + woff);
;       if (kt + 4 < nk) gemm_gload(g, A0, lda0, A1, lda1, ksplit, Bt, ldb, (kt + 4) * 32, tid);
;       __syncthreads();
;     }
;   }
.LBB0_2699:
	s_cmp_lt_i32 s91, 26
	s_cbranch_scc1 .Lfp5_fast
	s_add_i32 s91, s91, 2
	s_cmp_gt_u32 s91, 28
	ds_read_b128 v[208:211], v183
	ds_read_b128 v[232:235], v185 offset:16384
	ds_read_b128 v[236:239], v185 offset:18432
	ds_read_b128 v[240:243], v183 offset:2048
	ds_read_b128 v[252:255], v227 offset:16384
	s_waitcnt lgkmcnt(3)
	v_mfma_f32_32x32x16_bf16 v[112:127], v[208:211], v[232:235], v[112:127]
	s_waitcnt lgkmcnt(2)
	v_mfma_f32_32x32x16_bf16 v[96:111], v[208:211], v[236:239], v[96:111]
	ds_read_b128 v[208:211], v183 offset:4096
	s_waitcnt lgkmcnt(2)
	v_mfma_f32_32x32x16_bf16 v[80:95], v[240:243], v[232:235], v[80:95]
	v_mfma_f32_32x32x16_bf16 v[64:79], v[240:243], v[236:239], v[64:79]
	ds_read_b128 v[240:243], v183 offset:6144
	s_waitcnt lgkmcnt(1)
	v_mfma_f32_32x32x16_bf16 v[48:63], v[208:211], v[232:235], v[48:63]
	v_mfma_f32_32x32x16_bf16 v[32:47], v[208:211], v[236:239], v[32:47]
	ds_read_b128 v[208:211], v187
	s_waitcnt lgkmcnt(1)
	v_mfma_f32_32x32x16_bf16 v[0:15], v[240:243], v[236:239], v[0:15]
	ds_read_b128 v[236:239], v227 offset:18432
	v_mfma_f32_32x32x16_bf16 v[16:31], v[240:243], v[232:235], v[16:31]
	ds_read_b128 v[240:243], v187 offset:2048
	s_waitcnt lgkmcnt(2)
	v_mfma_f32_32x32x16_bf16 v[112:127], v[208:211], v[252:255], v[112:127]
	s_waitcnt lgkmcnt(1)
	v_mfma_f32_32x32x16_bf16 v[96:111], v[208:211], v[236:239], v[96:111]
	ds_read_b128 v[208:211], v187 offset:4096
	s_waitcnt lgkmcnt(1)
	v_mfma_f32_32x32x16_bf16 v[80:95], v[240:243], v[252:255], v[80:95]
	v_mfma_f32_32x32x16_bf16 v[64:79], v[240:243], v[236:239], v[64:79]
	ds_read_b128 v[240:243], v187 offset:6144
	s_waitcnt vmcnt(5)
	ds_write_b128 v179, v[128:131] offset:24576
	s_waitcnt vmcnt(4)
	ds_write_b128 v179, v[132:135] offset:28672
	s_waitcnt vmcnt(3)
	ds_write_b128 v179, v[144:147] offset:32768
	s_waitcnt vmcnt(2)
	ds_write_b128 v179, v[148:151] offset:36864
	s_waitcnt vmcnt(1)
	ds_write_b128 v179, v[160:163] offset:40960
	s_waitcnt vmcnt(0)
	ds_write_b128 v179, v[168:171] offset:45056
	s_waitcnt lgkmcnt(7)
	v_mfma_f32_32x32x16_bf16 v[48:63], v[208:211], v[252:255], v[48:63]
	v_mfma_f32_32x32x16_bf16 v[32:47], v[208:211], v[236:239], v[32:47]
	v_lshl_add_u64 v[210:211], v[204:205], 0, v[200:201]
	v_lshl_add_u64 v[208:209], v[206:207], 0, v[200:201]
	s_waitcnt lgkmcnt(6)
	v_mfma_f32_32x32x16_bf16 v[16:31], v[240:243], v[252:255], v[16:31]
	v_mfma_f32_32x32x16_bf16 v[0:15], v[240:243], v[236:239], v[0:15]
	s_waitcnt lgkmcnt(0)
	s_cbranch_scc1 .LBB0_2701
	v_add_co_u32_e32 v128, vcc, 0x1b00000, v210
	s_nop 1
	v_addc_co_u32_e32 v129, vcc, 0, v211, vcc
	v_add_co_u32_e32 v132, vcc, 0x1b20000, v210
	s_nop 1
	v_addc_co_u32_e32 v133, vcc, 0, v211, vcc
	v_add_co_u32_e32 v144, vcc, 0x1b40000, v210
	global_load_dwordx4 v[128:131], v[128:129], off offset:192
	s_nop 0
	global_load_dwordx4 v[132:135], v[132:133], off offset:192
	v_addc_co_u32_e32 v145, vcc, 0, v211, vcc
	v_add_co_u32_e32 v148, vcc, 0x1b60000, v210
	s_nop 1
	v_addc_co_u32_e32 v149, vcc, 0, v211, vcc
	v_add_co_u32_e32 v160, vcc, 0x200000, v208
	global_load_dwordx4 v[144:147], v[144:145], off offset:192
	s_nop 0
	global_load_dwordx4 v[148:151], v[148:149], off offset:192
	v_addc_co_u32_e32 v161, vcc, 0, v209, vcc
	v_add_co_u32_e32 v168, vcc, 0x220000, v208
	s_nop 1
	v_addc_co_u32_e32 v169, vcc, 0, v209, vcc
	global_load_dwordx4 v[160:163], v[160:161], off offset:192
	s_nop 0
	global_load_dwordx4 v[168:171], v[168:169], off offset:192

; template <bool RES, class Epi>
; DEV void gemm_tile_x(const bf16_t* A0, int lda0, const bf16_t* A1, int lda1, int ksplit,
;                      const bf16_t* Bt, int ldb, int K, char* smem, const float* resb, Epi epi) {
;     ...
;   for (int kt = 0; kt < nk; kt += 2) {
;     GEMM_COMPUTE(sbase);
;     if (kt + 1 < nk) gemm_lds_write(g1, sbase + GST + woff, sbase + GST + GSA + woff);
;     if (kt + 3 < nk) gemm_gload(g1, A0, lda0, A1, lda1, ksplit, Bt, ldb, (kt + 3) * 32, tid);
;     __syncthreads();
;     if (kt + 1 < nk) {
;       GEMM_COMPUTE(sbase + GST);
;       if (kt + 2 < nk) gemm_lds_write(g, sbase + woff, sbase + GSA + woff);
;       if (kt + 4 < nk) gemm_gload(g, A0, lda0, A1, lda1, ksplit, Bt, ldb, (kt + 4) * 32, tid);
;       __syncthreads();
;     }
;   }
.Lfp5_fast:
	s_add_i32 s91, s91, 2
	v_lshl_add_u64 v[252:253], v[204:205], 0, v[200:201]
	v_lshl_add_u64 v[254:255], v[206:207], 0, v[200:201]
	s_mov_b32 vcc_hi, 0
	ds_read_b128 v[208:211], v183
	ds_read_b128 v[232:235], v185 offset:16384
	ds_read_b128 v[236:239], v185 offset:18432
	ds_read_b128 v[240:243], v183 offset:2048
	s_waitcnt lgkmcnt(2)
	v_mfma_f32_32x32x16_bf16 v[112:127], v[208:211], v[232:235], v[112:127]
	s_waitcnt lgkmcnt(1)
	v_mfma_f32_32x32x16_bf16 v[96:111], v[208:211], v[236:239], v[96:111]
	ds_read_b128 v[208:211], v183 offset:4096
	s_waitcnt vmcnt(5)
	ds_write_b128 v179, v[128:131] offset:24576
	s_waitcnt vmcnt(4)
	ds_write_b128 v179, v[132:135] offset:28672
	s_waitcnt lgkmcnt(3)
	v_mfma_f32_32x32x16_bf16 v[80:95], v[240:243], v[232:235], v[80:95]
	v_mfma_f32_32x32x16_bf16 v[64:79], v[240:243], v[236:239], v[64:79]
	ds_read_b128 v[240:243], v183 offset:6144
	s_waitcnt vmcnt(3)
	ds_write_b128 v179, v[144:147] offset:32768
	s_waitcnt vmcnt(2)
	ds_write_b128 v179, v[148:151] offset:36864
	s_waitcnt lgkmcnt(5)
	v_mfma_f32_32x32x16_bf16 v[48:63], v[208:211], v[232:235], v[48:63]
	v_mfma_f32_32x32x16_bf16 v[32:47], v[208:211], v[236:239], v[32:47]
	ds_read_b128 v[208:211], v187
	s_waitcnt vmcnt(1)
	ds_write_b128 v179, v[160:163] offset:40960
	s_waitcnt vmcnt(0)
	ds_write_b128 v179, v[168:171] offset:45056
	s_waitcnt lgkmcnt(5)
	v_mfma_f32_32x32x16_bf16 v[16:31], v[240:243], v[232:235], v[16:31]
	ds_read_b128 v[232:235], v227 offset:16384
	v_mfma_f32_32x32x16_bf16 v[0:15], v[240:243], v[236:239], v[0:15]
	ds_read_b128 v[236:239], v227 offset:18432
	ds_read_b128 v[240:243], v187 offset:2048
	s_waitcnt lgkmcnt(2)
	v_mfma_f32_32x32x16_bf16 v[112:127], v[208:211], v[232:235], v[112:127]
	s_waitcnt lgkmcnt(1)
	v_mfma_f32_32x32x16_bf16 v[96:111], v[208:211], v[236:239], v[96:111]
	ds_read_b128 v[208:211], v187 offset:4096
	s_mov_b32 vcc_lo, 0x1b00000
	v_lshl_add_u64 v[128:129], v[252:253], 0, vcc
	global_load_dwordx4 v[128:131], v[128:129], off offset:192
	s_mov_b32 vcc_lo, 0x1b20000
	v_lshl_add_u64 v[132:133], v[252:253], 0, vcc
	global_load_dwordx4 v[132:135], v[132:133], off offset:192
	s_waitcnt lgkmcnt(1)
	v_mfma_f32_32x32x16_bf16 v[80:95], v[240:243], v[232:235], v[80:95]
	v_mfma_f32_32x32x16_bf16 v[64:79], v[240:243], v[236:239], v[64:79]
	ds_read_b128 v[240:243], v187 offset:6144
	s_mov_b32 vcc_lo, 0x1b40000
	v_lshl_add_u64 v[144:145], v[252:253], 0, vcc
	global_load_dwordx4 v[144:147], v[144:145], off offset:192
	s_mov_b32 vcc_lo, 0x1b60000
	v_lshl_add_u64 v[148:149], v[252:253], 0, vcc
	global_load_dwordx4 v[148:151], v[148:149], off offset:192
	s_waitcnt lgkmcnt(1)
	v_mfma_f32_32x32x16_bf16 v[48:63], v[208:211], v[232:235], v[48:63]
	v_mfma_f32_32x32x16_bf16 v[32:47], v[208:211], v[236:239], v[32:47]
	s_mov_b32 vcc_lo, 0x200000
	v_lshl_add_u64 v[160:161], v[254:255], 0, vcc
	global_load_dwordx4 v[160:163], v[160:161], off offset:192
	s_mov_b32 vcc_lo, 0x220000
	v_lshl_add_u64 v[168:169], v[254:255], 0, vcc
	global_load_dwordx4 v[168:171], v[168:169], off offset:192
	s_waitcnt lgkmcnt(0)
	v_mfma_f32_32x32x16_bf16 v[16:31], v[240:243], v[232:235], v[16:31]
	v_mfma_f32_32x32x16_bf16 v[0:15], v[240:243], v[236:239], v[0:15]
	s_waitcnt lgkmcnt(0)
	s_barrier
	ds_read_b128 v[208:211], v183 offset:24576
	ds_read_b128 v[232:235], v185 offset:40960
	ds_read_b128 v[236:239], v185 offset:43008
	ds_read_b128 v[240:243], v183 offset:26624
	s_waitcnt lgkmcnt(2)
	v_mfma_f32_32x32x16_bf16 v[112:127], v[208:211], v[232:235], v[112:127]
	s_waitcnt lgkmcnt(1)
	v_mfma_f32_32x32x16_bf16 v[96:111], v[208:211], v[236:239], v[96:111]
	ds_read_b128 v[208:211], v183 offset:28672
	ds_write_b128 v179, v[140:143]
	ds_write_b128 v179, v[136:139] offset:4096
	s_waitcnt lgkmcnt(3)
	v_mfma_f32_32x32x16_bf16 v[80:95], v[240:243], v[232:235], v[80:95]
	v_mfma_f32_32x32x16_bf16 v[64:79], v[240:243], v[236:239], v[64:79]
	ds_read_b128 v[240:243], v183 offset:30720
	ds_write_b128 v179, v[152:155] offset:8192
	ds_write_b128 v179, v[156:159] offset:12288
	s_waitcnt lgkmcnt(5)
	v_mfma_f32_32x32x16_bf16 v[48:63], v[208:211], v[232:235], v[48:63]
	v_mfma_f32_32x32x16_bf16 v[32:47], v[208:211], v[236:239], v[32:47]
	ds_read_b128 v[208:211], v187 offset:24576
	ds_write_b128 v179, v[164:167] offset:16384
	ds_write_b128 v179, v[172:175] offset:20480
	s_waitcnt lgkmcnt(5)
	v_mfma_f32_32x32x16_bf16 v[16:31], v[240:243], v[232:235], v[16:31]
	ds_read_b128 v[232:235], v227 offset:40960
	v_mfma_f32_32x32x16_bf16 v[0:15], v[240:243], v[236:239], v[0:15]
	ds_read_b128 v[236:239], v227 offset:43008
	ds_read_b128 v[240:243], v187 offset:26624
	s_waitcnt lgkmcnt(2)
	v_mfma_f32_32x32x16_bf16 v[112:127], v[208:211], v[232:235], v[112:127]
	s_waitcnt lgkmcnt(1)
	v_mfma_f32_32x32x16_bf16 v[96:111], v[208:211], v[236:239], v[96:111]
	ds_read_b128 v[208:211], v187 offset:28672
	s_mov_b32 vcc_lo, 0x1b00000
	v_lshl_add_u64 v[140:141], v[252:253], 0, vcc
	global_load_dwordx4 v[140:143], v[140:141], off offset:256
	s_mov_b32 vcc_lo, 0x1b20000
	v_lshl_add_u64 v[136:137], v[252:253], 0, vcc
	global_load_dwordx4 v[136:139], v[136:137], off offset:256
	s_waitcnt lgkmcnt(1)
	v_mfma_f32_32x32x16_bf16 v[80:95], v[240:243], v[232:235], v[80:95]
	v_mfma_f32_32x32x16_bf16 v[64:79], v[240:243], v[236:239], v[64:79]
	ds_read_b128 v[240:243], v187 offset:30720
	s_mov_b32 vcc_lo, 0x1b40000
	v_lshl_add_u64 v[152:153], v[252:253], 0, vcc
	global_load_dwordx4 v[152:155], v[152:153], off offset:256
	s_mov_b32 vcc_lo, 0x1b60000
	v_lshl_add_u64 v[156:157], v[252:253], 0, vcc
	global_load_dwordx4 v[156:159], v[156:157], off offset:256
	s_waitcnt lgkmcnt(1)
	v_mfma_f32_32x32x16_bf16 v[48:63], v[208:211], v[232:235], v[48:63]
	v_mfma_f32_32x32x16_bf16 v[32:47], v[208:211], v[236:239], v[32:47]
	s_mov_b32 vcc_lo, 0x200000
	v_lshl_add_u64 v[164:165], v[254:255], 0, vcc
	global_load_dwordx4 v[164:167], v[164:165], off offset:256
	s_mov_b32 vcc_lo, 0x220000
	v_lshl_add_u64 v[172:173], v[254:255], 0, vcc
	global_load_dwordx4 v[172:175], v[172:173], off offset:256
	s_waitcnt lgkmcnt(0)
	v_mfma_f32_32x32x16_bf16 v[16:31], v[240:243], v[232:235], v[16:31]
	v_mfma_f32_32x32x16_bf16 v[0:15], v[240:243], v[236:239], v[0:15]
	v_lshl_add_u64 v[206:207], v[206:207], 0, s[52:53]
	v_lshl_add_u64 v[204:205], v[204:205], 0, s[52:53]
	s_waitcnt lgkmcnt(0)
	s_barrier
	s_branch .LBB0_2699

; template <bool RES, class Epi>
; DEV void gemm_tile_x(const bf16_t* A0, int lda0, const bf16_t* A1, int lda1, int ksplit,
;                      const bf16_t* Bt, int ldb, int K, char* smem, const float* resb, Epi epi) {
;     ...
;   for (int kt = 0; kt < nk; kt += 2) {
;     GEMM_COMPUTE(sbase);
;     if (kt + 1 < nk) gemm_lds_write(g1, sbase + GST + woff, sbase + GST + GSA + woff);
;     if (kt + 3 < nk) gemm_gload(g1, A0, lda0, A1, lda1, ksplit, Bt, ldb, (kt + 3) * 32, tid);
;     __syncthreads();
;     if (kt + 1 < nk) {
;       GEMM_COMPUTE(sbase + GST);
;       if (kt + 2 < nk) gemm_lds_write(g, sbase + woff, sbase + GSA + woff);
;       if (kt + 4 < nk) gemm_gload(g, A0, lda0, A1, lda1, ksplit, Bt, ldb, (kt + 4) * 32, tid);
;       __syncthreads();
;     }
;   }
.LBB0_3035:
	s_cmp_lt_i32 s58, 26
	s_cbranch_scc1 .Lfp8_fast
	s_add_i32 s58, s58, 2
	s_cmp_gt_u32 s58, 28
	ds_read_b128 v[198:201], v183
	ds_read_b128 v[210:213], v202 offset:16384
	ds_read_b128 v[228:231], v202 offset:18432
	ds_read_b128 v[232:235], v183 offset:2048
	ds_read_b128 v[252:255], v204 offset:16384
	s_waitcnt lgkmcnt(3)
	v_mfma_f32_32x32x16_bf16 v[112:127], v[198:201], v[210:213], v[112:127]
	s_waitcnt lgkmcnt(2)
	v_mfma_f32_32x32x16_bf16 v[96:111], v[198:201], v[228:231], v[96:111]
	ds_read_b128 v[198:201], v183 offset:4096
	s_waitcnt lgkmcnt(2)
	v_mfma_f32_32x32x16_bf16 v[80:95], v[232:235], v[210:213], v[80:95]
	v_mfma_f32_32x32x16_bf16 v[64:79], v[232:235], v[228:231], v[64:79]
	ds_read_b128 v[232:235], v183 offset:6144
	s_waitcnt lgkmcnt(1)
	v_mfma_f32_32x32x16_bf16 v[48:63], v[198:201], v[210:213], v[48:63]
	v_mfma_f32_32x32x16_bf16 v[32:47], v[198:201], v[228:231], v[32:47]
	ds_read_b128 v[198:201], v203
	s_waitcnt lgkmcnt(1)
	v_mfma_f32_32x32x16_bf16 v[0:15], v[232:235], v[228:231], v[0:15]
	ds_read_b128 v[228:231], v204 offset:18432
	v_mfma_f32_32x32x16_bf16 v[16:31], v[232:235], v[210:213], v[16:31]
	ds_read_b128 v[232:235], v203 offset:2048
	s_waitcnt lgkmcnt(2)
	v_mfma_f32_32x32x16_bf16 v[112:127], v[198:201], v[252:255], v[112:127]
	s_waitcnt lgkmcnt(1)
	v_mfma_f32_32x32x16_bf16 v[96:111], v[198:201], v[228:231], v[96:111]
	ds_read_b128 v[198:201], v203 offset:4096
	s_waitcnt lgkmcnt(1)
	v_mfma_f32_32x32x16_bf16 v[80:95], v[232:235], v[252:255], v[80:95]
	v_mfma_f32_32x32x16_bf16 v[64:79], v[232:235], v[228:231], v[64:79]
	ds_read_b128 v[232:235], v203 offset:6144
	s_waitcnt vmcnt(5)
	ds_write_b128 v179, v[128:131] offset:24576
	s_waitcnt vmcnt(4)
	ds_write_b128 v179, v[132:135] offset:28672
	s_waitcnt vmcnt(3)
	ds_write_b128 v179, v[144:147] offset:32768
	s_waitcnt vmcnt(2)
	ds_write_b128 v179, v[148:151] offset:36864
	s_waitcnt vmcnt(1)
	ds_write_b128 v179, v[160:163] offset:40960
	s_waitcnt vmcnt(0)
	ds_write_b128 v179, v[168:171] offset:45056
	s_waitcnt lgkmcnt(7)
	v_mfma_f32_32x32x16_bf16 v[48:63], v[198:201], v[252:255], v[48:63]
	v_mfma_f32_32x32x16_bf16 v[32:47], v[198:201], v[228:231], v[32:47]
	v_lshl_add_u64 v[200:201], v[194:195], 0, v[192:193]
	v_lshl_add_u64 v[198:199], v[196:197], 0, v[192:193]
	s_waitcnt lgkmcnt(6)
	v_mfma_f32_32x32x16_bf16 v[16:31], v[232:235], v[252:255], v[16:31]
	v_mfma_f32_32x32x16_bf16 v[0:15], v[232:235], v[228:231], v[0:15]
	s_waitcnt lgkmcnt(0)
	s_cbranch_scc1 .LBB0_3037
	v_add_co_u32_e32 v128, vcc, 0x1b00000, v200
	s_nop 1
	v_addc_co_u32_e32 v129, vcc, 0, v201, vcc
	v_add_co_u32_e32 v132, vcc, 0x1b20000, v200
	s_nop 1
	v_addc_co_u32_e32 v133, vcc, 0, v201, vcc
	v_add_co_u32_e32 v144, vcc, 0x1b40000, v200
	global_load_dwordx4 v[128:131], v[128:129], off offset:192
	s_nop 0
	global_load_dwordx4 v[132:135], v[132:133], off offset:192
	v_addc_co_u32_e32 v145, vcc, 0, v201, vcc
	v_add_co_u32_e32 v148, vcc, 0x1b60000, v200
	s_nop 1
	v_addc_co_u32_e32 v149, vcc, 0, v201, vcc
	v_add_co_u32_e32 v160, vcc, 0x800000, v198
	global_load_dwordx4 v[144:147], v[144:145], off offset:192
	s_nop 0
	global_load_dwordx4 v[148:151], v[148:149], off offset:192
	v_addc_co_u32_e32 v161, vcc, 0, v199, vcc
	v_add_co_u32_e32 v168, vcc, 0x820000, v198
	s_nop 1
	v_addc_co_u32_e32 v169, vcc, 0, v199, vcc
	global_load_dwordx4 v[160:163], v[160:161], off offset:192
	s_nop 0
	global_load_dwordx4 v[168:171], v[168:169], off offset:192

; template <bool RES, class Epi>
; DEV void gemm_tile_x(const bf16_t* A0, int lda0, const bf16_t* A1, int lda1, int ksplit,
;                      const bf16_t* Bt, int ldb, int K, char* smem, const float* resb, Epi epi) {
;     ...
;   for (int kt = 0; kt < nk; kt += 2) {
;     GEMM_COMPUTE(sbase);
;     if (kt + 1 < nk) gemm_lds_write(g1, sbase + GST + woff, sbase + GST + GSA + woff);
;     if (kt + 3 < nk) gemm_gload(g1, A0, lda0, A1, lda1, ksplit, Bt, ldb, (kt + 3) * 32, tid);
;     __syncthreads();
;     if (kt + 1 < nk) {
;       GEMM_COMPUTE(sbase + GST);
;       if (kt + 2 < nk) gemm_lds_write(g, sbase + woff, sbase + GSA + woff);
;       if (kt + 4 < nk) gemm_gload(g, A0, lda0, A1, lda1, ksplit, Bt, ldb, (kt + 4) * 32, tid);
;       __syncthreads();
;     }
;   }
.Lfp8_fast:
	s_add_i32 s58, s58, 2
	v_lshl_add_u64 v[252:253], v[194:195], 0, v[192:193]
	v_lshl_add_u64 v[254:255], v[196:197], 0, v[192:193]
	s_mov_b32 vcc_hi, 0
	ds_read_b128 v[198:201], v183
	ds_read_b128 v[210:213], v202 offset:16384
	ds_read_b128 v[228:231], v202 offset:18432
	ds_read_b128 v[232:235], v183 offset:2048
	s_waitcnt lgkmcnt(2)
	v_mfma_f32_32x32x16_bf16 v[112:127], v[198:201], v[210:213], v[112:127]
	s_waitcnt lgkmcnt(1)
	v_mfma_f32_32x32x16_bf16 v[96:111], v[198:201], v[228:231], v[96:111]
	ds_read_b128 v[198:201], v183 offset:4096
	s_waitcnt vmcnt(5)
	ds_write_b128 v179, v[128:131] offset:24576
	s_waitcnt vmcnt(4)
	ds_write_b128 v179, v[132:135] offset:28672
	s_waitcnt lgkmcnt(3)
	v_mfma_f32_32x32x16_bf16 v[80:95], v[232:235], v[210:213], v[80:95]
	v_mfma_f32_32x32x16_bf16 v[64:79], v[232:235], v[228:231], v[64:79]
	ds_read_b128 v[232:235], v183 offset:6144
	s_waitcnt vmcnt(3)
	ds_write_b128 v179, v[144:147] offset:32768
	s_waitcnt vmcnt(2)
	ds_write_b128 v179, v[148:151] offset:36864
	s_waitcnt lgkmcnt(5)
	v_mfma_f32_32x32x16_bf16 v[48:63], v[198:201], v[210:213], v[48:63]
	v_mfma_f32_32x32x16_bf16 v[32:47], v[198:201], v[228:231], v[32:47]
	ds_read_b128 v[198:201], v203
	s_waitcnt vmcnt(1)
	ds_write_b128 v179, v[160:163] offset:40960
	s_waitcnt vmcnt(0)
	ds_write_b128 v179, v[168:171] offset:45056
	s_waitcnt lgkmcnt(5)
	v_mfma_f32_32x32x16_bf16 v[16:31], v[232:235], v[210:213], v[16:31]
	ds_read_b128 v[210:213], v204 offset:16384
	v_mfma_f32_32x32x16_bf16 v[0:15], v[232:235], v[228:231], v[0:15]
	ds_read_b128 v[228:231], v204 offset:18432
	ds_read_b128 v[232:235], v203 offset:2048
	s_waitcnt lgkmcnt(2)
	v_mfma_f32_32x32x16_bf16 v[112:127], v[198:201], v[210:213], v[112:127]
	s_waitcnt lgkmcnt(1)
	v_mfma_f32_32x32x16_bf16 v[96:111], v[198:201], v[228:231], v[96:111]
	ds_read_b128 v[198:201], v203 offset:4096
	s_mov_b32 vcc_lo, 0x1b00000
	v_lshl_add_u64 v[128:129], v[252:253], 0, vcc
	global_load_dwordx4 v[128:131], v[128:129], off offset:192
	s_mov_b32 vcc_lo, 0x1b20000
	v_lshl_add_u64 v[132:133], v[252:253], 0, vcc
	global_load_dwordx4 v[132:135], v[132:133], off offset:192
	s_waitcnt lgkmcnt(1)
	v_mfma_f32_32x32x16_bf16 v[80:95], v[232:235], v[210:213], v[80:95]
	v_mfma_f32_32x32x16_bf16 v[64:79], v[232:235], v[228:231], v[64:79]
	ds_read_b128 v[232:235], v203 offset:6144
	s_mov_b32 vcc_lo, 0x1b40000
	v_lshl_add_u64 v[144:145], v[252:253], 0, vcc
	global_load_dwordx4 v[144:147], v[144:145], off offset:192
	s_mov_b32 vcc_lo, 0x1b60000
	v_lshl_add_u64 v[148:149], v[252:253], 0, vcc
	global_load_dwordx4 v[148:151], v[148:149], off offset:192
	s_waitcnt lgkmcnt(1)
	v_mfma_f32_32x32x16_bf16 v[48:63], v[198:201], v[210:213], v[48:63]
	v_mfma_f32_32x32x16_bf16 v[32:47], v[198:201], v[228:231], v[32:47]
	s_mov_b32 vcc_lo, 0x800000
	v_lshl_add_u64 v[160:161], v[254:255], 0, vcc
	global_load_dwordx4 v[160:163], v[160:161], off offset:192
	s_mov_b32 vcc_lo, 0x820000
	v_lshl_add_u64 v[168:169], v[254:255], 0, vcc
	global_load_dwordx4 v[168:171], v[168:169], off offset:192
	s_waitcnt lgkmcnt(0)
	v_mfma_f32_32x32x16_bf16 v[16:31], v[232:235], v[210:213], v[16:31]
	v_mfma_f32_32x32x16_bf16 v[0:15], v[232:235], v[228:231], v[0:15]
	s_waitcnt lgkmcnt(0)
	s_barrier
	ds_read_b128 v[198:201], v183 offset:24576
	ds_read_b128 v[210:213], v202 offset:40960
	ds_read_b128 v[228:231], v202 offset:43008
	ds_read_b128 v[232:235], v183 offset:26624
	s_waitcnt lgkmcnt(2)
	v_mfma_f32_32x32x16_bf16 v[112:127], v[198:201], v[210:213], v[112:127]
	s_waitcnt lgkmcnt(1)
	v_mfma_f32_32x32x16_bf16 v[96:111], v[198:201], v[228:231], v[96:111]
	ds_read_b128 v[198:201], v183 offset:28672
	ds_write_b128 v179, v[140:143]
	ds_write_b128 v179, v[136:139] offset:4096
	s_waitcnt lgkmcnt(3)
	v_mfma_f32_32x32x16_bf16 v[80:95], v[232:235], v[210:213], v[80:95]
	v_mfma_f32_32x32x16_bf16 v[64:79], v[232:235], v[228:231], v[64:79]
	ds_read_b128 v[232:235], v183 offset:30720
	ds_write_b128 v179, v[152:155] offset:8192
	ds_write_b128 v179, v[156:159] offset:12288
	s_waitcnt lgkmcnt(5)
	v_mfma_f32_32x32x16_bf16 v[48:63], v[198:201], v[210:213], v[48:63]
	v_mfma_f32_32x32x16_bf16 v[32:47], v[198:201], v[228:231], v[32:47]
	ds_read_b128 v[198:201], v203 offset:24576
	ds_write_b128 v179, v[164:167] offset:16384
	ds_write_b128 v179, v[172:175] offset:20480
	s_waitcnt lgkmcnt(5)
	v_mfma_f32_32x32x16_bf16 v[16:31], v[232:235], v[210:213], v[16:31]
	ds_read_b128 v[210:213], v204 offset:40960
	v_mfma_f32_32x32x16_bf16 v[0:15], v[232:235], v[228:231], v[0:15]
	ds_read_b128 v[228:231], v204 offset:43008
	ds_read_b128 v[232:235], v203 offset:26624
	s_waitcnt lgkmcnt(2)
	v_mfma_f32_32x32x16_bf16 v[112:127], v[198:201], v[210:213], v[112:127]
	s_waitcnt lgkmcnt(1)
	v_mfma_f32_32x32x16_bf16 v[96:111], v[198:201], v[228:231], v[96:111]
	ds_read_b128 v[198:201], v203 offset:28672
	s_mov_b32 vcc_lo, 0x1b00000
	v_lshl_add_u64 v[140:141], v[252:253], 0, vcc
	global_load_dwordx4 v[140:143], v[140:141], off offset:256
	s_mov_b32 vcc_lo, 0x1b20000
	v_lshl_add_u64 v[136:137], v[252:253], 0, vcc
	global_load_dwordx4 v[136:139], v[136:137], off offset:256
	s_waitcnt lgkmcnt(1)
	v_mfma_f32_32x32x16_bf16 v[80:95], v[232:235], v[210:213], v[80:95]
	v_mfma_f32_32x32x16_bf16 v[64:79], v[232:235], v[228:231], v[64:79]
	ds_read_b128 v[232:235], v203 offset:30720
	s_mov_b32 vcc_lo, 0x1b40000
	v_lshl_add_u64 v[152:153], v[252:253], 0, vcc
	global_load_dwordx4 v[152:155], v[152:153], off offset:256
	s_mov_b32 vcc_lo, 0x1b60000
	v_lshl_add_u64 v[156:157], v[252:253], 0, vcc
	global_load_dwordx4 v[156:159], v[156:157], off offset:256
	s_waitcnt lgkmcnt(1)
	v_mfma_f32_32x32x16_bf16 v[48:63], v[198:201], v[210:213], v[48:63]
	v_mfma_f32_32x32x16_bf16 v[32:47], v[198:201], v[228:231], v[32:47]
	s_mov_b32 vcc_lo, 0x800000
	v_lshl_add_u64 v[164:165], v[254:255], 0, vcc
	global_load_dwordx4 v[164:167], v[164:165], off offset:256
	s_mov_b32 vcc_lo, 0x820000
	v_lshl_add_u64 v[172:173], v[254:255], 0, vcc
	global_load_dwordx4 v[172:175], v[172:173], off offset:256
	s_waitcnt lgkmcnt(0)
	v_mfma_f32_32x32x16_bf16 v[16:31], v[232:235], v[210:213], v[16:31]
	v_mfma_f32_32x32x16_bf16 v[0:15], v[232:235], v[228:231], v[0:15]
	v_lshl_add_u64 v[196:197], v[196:197], 0, s[50:51]
	v_lshl_add_u64 v[194:195], v[194:195], 0, s[50:51]
	s_waitcnt lgkmcnt(0)
	s_barrier
	s_branch .LBB0_3035
